# stagger: half of the row-panel groups start the two fused-epilogue GEMM phases ~10 us late so the chip-wide epilogue memory bursts interleave with the other half's MFMA work, on top of v36
# baseline (speedup 1.0000x reference)
.LBB0_659:
	s_cmp_lt_i32 s28, 6
	s_cselect_b64 s[0:1], -1, 0
	s_cmp_gt_i32 s29, 5
	s_cselect_b64 s[2:3], -1, 0
	s_and_b64 s[0:1], s[0:1], s[2:3]
	s_andn2_b64 vcc, exec, s[0:1]
	s_cbranch_vccnz .LBB0_778
	s_bitcmp1_b32 s14, 6
	s_cbranch_scc0 .Lstag_p5_skip
	s_mov_b32 s99, 2
.Lstag_p5_dl:
	s_sleep 127
	s_sub_u32 s99, s99, 1
	s_cmp_lg_u32 s99, 0
	s_cbranch_scc1 .Lstag_p5_dl
.Lstag_p5_skip:
	v_mov_b32_e32 v1, 0
	global_load_dword v1, v1, s[74:75] sc1
	s_cmpk_eq_i32 s33, 0x100
	s_mov_b64 s[0:1], -1
	s_cbranch_scc1 .LBB0_665
	s_waitcnt vmcnt(0) lgkmcnt(0)
	v_or_b32_e32 v2, s14, v0
	v_cmp_eq_u32_e32 vcc, 0, v2
	s_and_saveexec_b64 s[0:1], vcc
	s_cbranch_execz .LBB0_663
	v_mov_b32_e32 v2, 0
	v_mov_b32_e32 v3, 0x7f0
	global_store_dword v2, v3, s[74:75] offset:4 sc1
	v_mov_b32_e32 v3, 1
	global_store_dword v2, v3, s[74:75] sc1

.LBB0_1032:
	s_cmp_lt_i32 s28, 9
	s_cselect_b64 s[0:1], -1, 0
	s_cmp_gt_i32 s29, 8
	s_cselect_b64 s[2:3], -1, 0
	s_and_b64 s[0:1], s[0:1], s[2:3]
	s_andn2_b64 vcc, exec, s[0:1]
	s_cbranch_vccnz .LBB0_1093
	s_bitcmp1_b32 s14, 6
	s_cbranch_scc0 .Lstag_p8_skip
	s_mov_b32 s99, 2

.Lstag_p8_skip:
	v_mov_b32_e32 v151, 0
	s_waitcnt vmcnt(0) lgkmcnt(0)
	v_mov_b32_e32 v2, 0x4000
	global_load_dword v1, v151, s[74:75] sc1
	s_cmpk_lg_i32 s33, 0x100
	global_load_dword v2, v2, s[74:75] offset:512 sc1
	s_cselect_b64 s[0:1], -1, 0
	s_waitcnt vmcnt(0)
	v_or_b32_e32 v1, v2, v1
	v_cmp_ne_u32_e32 vcc, 0, v1
	s_or_b64 s[0:1], s[0:1], vcc
	s_andn2_b64 vcc, exec, s[0:1]
	s_mov_b64 s[0:1], -1
	s_cbranch_vccz .LBB0_1089
	s_add_u32 s10, s74, 0x3a600000
	s_addc_u32 s11, s75, 0
	s_lshl_b32 s3, s14, 1
	v_lshlrev_b32_e32 v1, 4, v0
	v_and_b32_e32 v2, 32, v0
	v_bfe_u32 v3, v0, 2, 4
	v_lshrrev_b32_e32 v14, 3, v0
	s_and_b32 s3, s3, 12
	s_ashr_i32 s47, s14, 6
	s_lshl_b32 s4, s14, 3
	v_readfirstlane_b32 s0, v0
	v_bitop3_b32 v10, v1, v2, 48 bitop3:0x6c
	v_and_or_b32 v2, v14, 48, v3
	s_bfe_u32 s5, s14, 0x30003
	s_add_i32 s47, s47, s3
	s_and_b32 s3, s4, 8
	s_lshr_b32 s1, s0, 6
	v_mul_u32_u24_e32 v12, 0x5600, v2
	v_or_b32_e32 v2, 64, v14
	s_movk_i32 s2, 0x70
	s_or_b32 s12, s3, s5
	v_and_or_b32 v2, v2, s2, v3
	s_lshr_b32 s2, s0, 8
	s_lshl_b32 s46, s1, 10
	s_add_i32 s61, s47, 16
	s_mul_i32 s4, s12, 0x560000
	s_add_u32 s4, s74, s4
	s_addc_u32 s5, s75, 0
	v_and_b32_e32 v11, 64, v0
	s_add_u32 s22, s4, 0x13000000
	v_or_b32_e32 v1, v10, v11
	s_addc_u32 s23, s5, 0
	s_add_i32 s48, s46, 0
	v_or_b32_e32 v150, v12, v1
	s_add_i32 m0, s48, 0x10000
	v_mul_u32_u24_e32 v13, 0x5600, v2
	global_load_lds_dwordx4 v150, s[22:23]
	s_add_i32 m0, s48, 0x12000
	v_or_b32_e32 v152, v13, v1
	s_add_u32 s4, s4, 0x132b0000
	global_load_lds_dwordx4 v152, s[22:23]
	s_addc_u32 s5, s5, 0
	s_add_i32 m0, s48, 0x14000
	s_mul_i32 s6, s61, 0x560000
	global_load_lds_dwordx4 v150, s[4:5]
	s_add_i32 m0, s48, 0x16000
	s_mul_hi_i32 s3, s61, 0x560000
	s_add_u32 s24, s10, s6
	s_addc_u32 s25, s11, s3
	s_add_i32 s49, s48, 0x2000
	global_load_lds_dwordx4 v152, s[4:5]
	s_mov_b32 m0, s48
	s_add_u32 s4, s24, 0x2b0000
	global_load_lds_dwordx4 v150, s[24:25]
	s_mov_b32 m0, s49
	s_addc_u32 s5, s25, 0
	s_add_i32 s50, s48, 0x4000
	global_load_lds_dwordx4 v152, s[24:25]
	s_mov_b32 m0, s50
	s_add_i32 s51, s48, 0x6000
	global_load_lds_dwordx4 v150, s[4:5]
	s_mov_b32 m0, s51
	v_mov_b32_e32 v153, v151
	global_load_lds_dwordx4 v152, s[4:5]
	s_cmp_eq_u32 s2, 1
	s_mov_b32 s27, 1
	v_lshl_add_u64 v[8:9], s[22:23], 0, v[150:151]
	v_lshl_add_u64 v[6:7], s[22:23], 0, v[152:153]
	v_lshl_add_u64 v[2:3], s[24:25], 0, v[150:151]
	s_cselect_b64 s[28:29], -1, 0
	s_cmp_lg_u32 s2, 1
	v_lshl_add_u64 v[4:5], s[24:25], 0, v[152:153]
	s_cbranch_scc1 .LBB0_1036
	s_barrier
